# S5 pre pass: all table-fragment loads of the G' pass issued up front (one exposed latency instead of eight); vres block loops over row chunks (any grid size)
# speedup vs baseline: 1.0010x; 1.0010x over previous
; #define GAS __attribute__((address_space(1)))
; #define SB() __builtin_amdgcn_sched_barrier(0)
; template <bool POST>
; DI void s5_phase(const Frame& F, const CAS Args& a, int l, int first, int stride) {
;     ...
;         bf16x8 uf[4];
; #pragma unroll
;         for (int ks = 0; ks < 4; ++ks) uf[ks] = LDU(bf16x8, zb + 64 * ks, lzu);
;         f32x4 Ar[4], Ai[4];
; #pragma unroll
;         for (int m = 0; m < 4; ++m) { Ar[m] = *(const GAS f32x4*)((const float*)(tb + S5T_L8) + 16 * m + 4 * kg); Ai[m] = *(const GAS f32x4*)((const float*)(tb + S5T_L8) + 64 + 16 * m + 4 * kg); }
;         if (POST && w == 0) { const int p = lane; const float lnr = ((const GAS float*)(tb + S5T_LN))[p], lni = ((const GAS float*)(tb + S5T_LN))[64 + p];
;             float xr = 0.f, xi = 0.f;
;             for (int q0 = 0; q0 < ib; q0 += 4) { float tr[4], ti[4];
; #pragma unroll
;                 for (int u = 0; u < 4; ++u) { const int q = (q0 + u < ib) ? q0 + u : q0; tr[u] = TOT[q * 128 + p]; ti[u] = TOT[q * 128 + 64 + p]; }
;                 SB();
; #pragma unroll
;                 for (int u = 0; u < 4; ++u) if (q0 + u < ib) { const float t0 = lnr * xr - lni * xi + tr[u], t1 = lnr * xi + lni * xr + ti[u]; xr = t0; xi = t1; }
;                 SB(); }
;             X0[p] = xr; X0[64 + p] = xi; }
;         SB();
;         f32x4 Yr[4], Yi[4];
;         { bf16x8 gf[2][4];
; #pragma unroll
;           for (int ks = 0; ks < 4; ++ks) gf[0][ks] = LDU(bf16x8, tb + S5T_G + (0 * 4 + ks) * 1024, ltab);
; #pragma unroll
;           for (int mt = 0; mt < 8; ++mt) {
;               if (mt + 1 < 8) {
; #pragma unroll
;                   for (int ks = 0; ks < 4; ++ks) gf[(mt + 1) & 1][ks] = LDU(bf16x8, tb + S5T_G + ((mt + 1) * 4 + ks) * 1024, ltab); }
;               SB();
;               f32x4 acc = {0.f, 0.f, 0.f, 0.f};
; #pragma unroll
;               for (int ks = 0; ks < 4; ++ks) acc = __builtin_amdgcn_mfma_f32_16x16x32_bf16(gf[mt & 1][ks], uf[ks], acc, 0, 0, 0);
;               if (mt < 4) Yr[mt] = acc; else Yi[mt - 4] = acc;
;               SB(); } }
.LBB0_724:
	s_ashr_i32 s4, s73, 4
	s_ashr_i32 s5, s4, 31
	s_mul_i32 s13, s71, 48
	s_add_u32 s13, s13, s4
	s_mul_hi_u32 s14, s71, 48
	s_addc_u32 s14, s14, s5
	s_mul_i32 s14, s14, 0x1a400
	s_mul_hi_u32 s15, s13, 0x1a400
	s_add_i32 s15, s15, s14
	s_mul_i32 s13, s13, 0x1a400
	s_add_u32 s14, s1, s13
	s_addc_u32 s15, s6, s15
	s_and_b32 s13, s11, 0x780
	s_lshl_b32 s16, s13, 3
	v_readlane_b32 s17, v253, 51
	s_add_i32 s16, s16, s17
	s_ashr_i32 s17, s16, 31
	s_lshl_b32 s18, s0, 12
	s_lshl_b64 s[4:5], s[4:5], 19
	s_lshl_b64 s[16:17], s[16:17], 5
	s_add_u32 s4, s7, s4
	s_addc_u32 s5, s8, s5
	s_add_u32 s4, s4, s16
	v_mov_b32_e32 v60, v73
	v_mov_b32_e32 v0, v99
	v_mov_b32_e32 v1, v100
	v_mov_b32_e32 v2, v98
	s_addc_u32 s5, s5, s17
	v_lshlrev_b32_e32 v184, 2, v72
	global_load_dwordx4 v[16:19], v2, s[4:5]
	global_load_dwordx4 v[20:23], v2, s[4:5] offset:64
	global_load_dwordx4 v[24:27], v2, s[4:5] offset:128
	global_load_dwordx4 v[28:31], v2, s[4:5] offset:192
	v_lshl_add_u64 v[0:1], s[14:15], 0, v[184:185]
	s_mov_b64 s[4:5], 0x18000
	v_lshl_add_u64 v[2:3], v[0:1], 0, s[4:5]
	s_mov_b64 s[4:5], 0x18100
	s_waitcnt vmcnt(14)
	v_lshl_add_u64 v[4:5], v[0:1], 0, s[4:5]
	s_mov_b32 s4, 0x18000
	v_add_co_u32_e64 v0, s[4:5], s4, v0
	s_add_i32 s16, s18, 0
	s_nop 0
	v_addc_co_u32_e64 v1, s[4:5], 0, v1, s[4:5]
	global_load_dwordx4 v[32:35], v[0:1], off
	global_load_dwordx4 v[36:39], v[0:1], off offset:256
	global_load_dwordx4 v[40:43], v[2:3], off offset:64
	global_load_dwordx4 v[8:11], v[2:3], off offset:128
	global_load_dwordx4 v[44:47], v[4:5], off offset:64
	s_nop 0
	global_load_dwordx4 v[0:3], v[2:3], off offset:192
	s_nop 0
	global_load_dwordx4 v[12:15], v[4:5], off offset:128
	s_nop 0
	global_load_dwordx4 v[4:7], v[4:5], off offset:192
	v_mov_b32_e32 v61, v185
	global_load_dwordx4 v[126:129], v60, s[14:15]
	global_load_dwordx4 v[130:133], v60, s[14:15] offset:1024
	global_load_dwordx4 v[134:137], v60, s[14:15] offset:2048
	global_load_dwordx4 v[138:141], v60, s[14:15] offset:3072
	s_add_u32 s98, s14, 0x1000
	s_addc_u32 s99, s15, 0
	global_load_dwordx4 v[142:145], v60, s[98:99]
	global_load_dwordx4 v[146:149], v60, s[98:99] offset:1024
	global_load_dwordx4 v[150:153], v60, s[98:99] offset:2048
	global_load_dwordx4 v[154:157], v60, s[98:99] offset:3072
	s_add_u32 s98, s14, 0x2000
	s_addc_u32 s99, s15, 0
	global_load_dwordx4 v[158:161], v60, s[98:99]
	global_load_dwordx4 v[162:165], v60, s[98:99] offset:1024
	global_load_dwordx4 v[166:169], v60, s[98:99] offset:2048
	global_load_dwordx4 v[170:173], v60, s[98:99] offset:3072
	s_add_u32 s98, s14, 0x3000
	s_addc_u32 s99, s15, 0
	global_load_dwordx4 v[174:177], v60, s[98:99]
	global_load_dwordx4 v[178:181], v60, s[98:99] offset:1024
	global_load_dwordx4 v[196:199], v60, s[98:99] offset:2048
	global_load_dwordx4 v[200:203], v60, s[98:99] offset:3072
	s_add_u32 s98, s14, 0x4000
	s_addc_u32 s99, s15, 0
	global_load_dwordx4 v[204:207], v60, s[98:99]
	global_load_dwordx4 v[208:211], v60, s[98:99] offset:1024
	global_load_dwordx4 v[212:215], v60, s[98:99] offset:2048
	global_load_dwordx4 v[216:219], v60, s[98:99] offset:3072
	s_add_u32 s98, s14, 0x5000
	s_addc_u32 s99, s15, 0
	global_load_dwordx4 v[220:223], v60, s[98:99]
	global_load_dwordx4 v[234:237], v60, s[98:99] offset:1024
	global_load_dwordx4 v[238:241], v60, s[98:99] offset:2048
	global_load_dwordx4 v[242:245], v60, s[98:99] offset:3072
	s_add_u32 s98, s14, 0x6000
	s_addc_u32 s99, s15, 0
	global_load_dwordx4 v[246:249], v60, s[98:99]
	global_load_dwordx4 v[110:113], v60, s[98:99] offset:1024
	global_load_dwordx4 v[114:117], v60, s[98:99] offset:2048
	global_load_dwordx4 v[118:121], v60, s[98:99] offset:3072
	s_waitcnt vmcnt(27)
	v_mfma_f32_16x16x32_bf16 v[48:51], v[126:129], v[16:19], 0
	s_waitcnt vmcnt(26)
	v_mfma_f32_16x16x32_bf16 v[48:51], v[130:133], v[20:23], v[48:51]
	s_waitcnt vmcnt(25)
	v_mfma_f32_16x16x32_bf16 v[48:51], v[134:137], v[24:27], v[48:51]
	s_waitcnt vmcnt(24)
	v_mfma_f32_16x16x32_bf16 v[48:51], v[138:141], v[28:31], v[48:51]
	s_add_u32 s98, s14, 0x7000
	s_addc_u32 s99, s15, 0
	global_load_dwordx4 v[126:129], v60, s[98:99]
	global_load_dwordx4 v[130:133], v60, s[98:99] offset:1024
	global_load_dwordx4 v[134:137], v60, s[98:99] offset:2048
	global_load_dwordx4 v[138:141], v60, s[98:99] offset:3072
	s_waitcnt vmcnt(27)
	v_mfma_f32_16x16x32_bf16 v[64:67], v[142:145], v[16:19], 0
	s_waitcnt vmcnt(26)
	v_mfma_f32_16x16x32_bf16 v[64:67], v[146:149], v[20:23], v[64:67]
	s_waitcnt vmcnt(25)
	v_mfma_f32_16x16x32_bf16 v[64:67], v[150:153], v[24:27], v[64:67]
	s_waitcnt vmcnt(24)
	v_mfma_f32_16x16x32_bf16 v[64:67], v[154:157], v[28:31], v[64:67]
	s_waitcnt vmcnt(23)
	v_mfma_f32_16x16x32_bf16 v[52:55], v[158:161], v[16:19], 0
	s_waitcnt vmcnt(22)
	v_mfma_f32_16x16x32_bf16 v[52:55], v[162:165], v[20:23], v[52:55]
	s_waitcnt vmcnt(21)
	v_mfma_f32_16x16x32_bf16 v[52:55], v[166:169], v[24:27], v[52:55]
	s_waitcnt vmcnt(20)
	v_mfma_f32_16x16x32_bf16 v[52:55], v[170:173], v[28:31], v[52:55]
	s_waitcnt vmcnt(19)
	v_mfma_f32_16x16x32_bf16 v[68:71], v[174:177], v[16:19], 0
	s_waitcnt vmcnt(18)
	v_mfma_f32_16x16x32_bf16 v[68:71], v[178:181], v[20:23], v[68:71]
	s_waitcnt vmcnt(17)
	v_mfma_f32_16x16x32_bf16 v[68:71], v[196:199], v[24:27], v[68:71]
	s_waitcnt vmcnt(16)
	v_mfma_f32_16x16x32_bf16 v[68:71], v[200:203], v[28:31], v[68:71]
	s_waitcnt vmcnt(15)
	v_mfma_f32_16x16x32_bf16 v[56:59], v[204:207], v[16:19], 0
	s_waitcnt vmcnt(14)
	v_mfma_f32_16x16x32_bf16 v[56:59], v[208:211], v[20:23], v[56:59]
	s_waitcnt vmcnt(13)
	v_mfma_f32_16x16x32_bf16 v[56:59], v[212:215], v[24:27], v[56:59]
	s_waitcnt vmcnt(12)
	v_mfma_f32_16x16x32_bf16 v[56:59], v[216:219], v[28:31], v[56:59]
	s_waitcnt vmcnt(11)
; #define SB() __builtin_amdgcn_sched_barrier(0)
; template <int CTRL> DI f32x4 dpp4(const f32x4 v) { const float a0 = v[0], a1 = v[1], a2 = v[2], a3 = v[3]; const float b0 = DPPF(a0, CTRL), b1 = DPPF(a1, CTRL), b2 = DPPF(a2, CTRL), b3 = DPPF(a3, CTRL); return (f32x4){b0, b1, b2, b3}; }
; template <int D>
; DI void s5_scan_step(f32x4 (&Yr)[4], f32x4 (&Yi)[4], f32x4 (&Ar)[4], f32x4 (&Ai)[4]) {
; #pragma unroll
;     for (int m = 0; m < 4; ++m) {
;         const f32x4 sr = dpp4<0x110 + D>(Yr[m]), si = dpp4<0x110 + D>(Yi[m]);
;         Yr[m] += Ar[m] * sr - Ai[m] * si; Yi[m] += Ar[m] * si + Ai[m] * sr;
;         const f32x4 a2r = Ar[m] * Ar[m] - Ai[m] * Ai[m], a2i = 2.f * Ar[m] * Ai[m]; Ar[m] = a2r; Ai[m] = a2i; }
; }
; template <bool POST>
; DI void s5_phase(const Frame& F, const CAS Args& a, int l, int first, int stride) {
;     ...
;           for (int mt = 0; mt < 8; ++mt) {
;               if (mt + 1 < 8) {
; #pragma unroll
;                   for (int ks = 0; ks < 4; ++ks) gf[(mt + 1) & 1][ks] = LDU(bf16x8, tb + S5T_G + ((mt + 1) * 4 + ks) * 1024, ltab); }
;               SB();
;               f32x4 acc = {0.f, 0.f, 0.f, 0.f};
; #pragma unroll
;               for (int ks = 0; ks < 4; ++ks) acc = __builtin_amdgcn_mfma_f32_16x16x32_bf16(gf[mt & 1][ks], uf[ks], acc, 0, 0, 0);
;               if (mt < 4) Yr[mt] = acc; else Yi[mt - 4] = acc;
;               SB(); } }
	v_mfma_f32_16x16x32_bf16 v[74:77], v[220:223], v[16:19], 0
	s_waitcnt vmcnt(10)
	v_mfma_f32_16x16x32_bf16 v[74:77], v[234:237], v[20:23], v[74:77]
	s_waitcnt vmcnt(9)
	v_mfma_f32_16x16x32_bf16 v[74:77], v[238:241], v[24:27], v[74:77]
	s_waitcnt vmcnt(8)
	v_mfma_f32_16x16x32_bf16 v[74:77], v[242:245], v[28:31], v[74:77]
	s_waitcnt vmcnt(7)
	v_mfma_f32_16x16x32_bf16 v[60:63], v[246:249], v[16:19], 0
	s_waitcnt vmcnt(6)
	v_mfma_f32_16x16x32_bf16 v[60:63], v[110:113], v[20:23], v[60:63]
	s_waitcnt vmcnt(5)
	v_mfma_f32_16x16x32_bf16 v[60:63], v[114:117], v[24:27], v[60:63]
	s_waitcnt vmcnt(4)
	v_mfma_f32_16x16x32_bf16 v[60:63], v[118:121], v[28:31], v[60:63]
	s_waitcnt vmcnt(3)
	v_mfma_f32_16x16x32_bf16 v[16:19], v[126:129], v[16:19], 0
	s_waitcnt vmcnt(2)
	v_mfma_f32_16x16x32_bf16 v[16:19], v[130:133], v[20:23], v[16:19]
	s_waitcnt vmcnt(1)
	v_mfma_f32_16x16x32_bf16 v[16:19], v[134:137], v[24:27], v[16:19]
	s_waitcnt vmcnt(0)
	v_mfma_f32_16x16x32_bf16 v[20:23], v[138:141], v[28:31], v[16:19]
	v_mov_b32_dpp v24, v56 row_shr:1 row_mask:0xf bank_mask:0xf bound_ctrl:1
	v_mov_b32_dpp v25, v57 row_shr:1 row_mask:0xf bank_mask:0xf bound_ctrl:1
	v_mov_b32_dpp v26, v58 row_shr:1 row_mask:0xf bank_mask:0xf bound_ctrl:1
	v_mov_b32_dpp v27, v59 row_shr:1 row_mask:0xf bank_mask:0xf bound_ctrl:1
	s_nop 1
	v_mov_b32_dpp v16, v48 row_shr:1 row_mask:0xf bank_mask:0xf bound_ctrl:1
	v_mov_b32_dpp v17, v49 row_shr:1 row_mask:0xf bank_mask:0xf bound_ctrl:1
	v_mov_b32_dpp v18, v50 row_shr:1 row_mask:0xf bank_mask:0xf bound_ctrl:1
	v_mov_b32_dpp v19, v51 row_shr:1 row_mask:0xf bank_mask:0xf bound_ctrl:1
	v_pk_mul_f32 v[28:29], v[38:39], v[26:27]
	v_pk_mul_f32 v[30:31], v[36:37], v[24:25]
	v_pk_mul_f32 v[26:27], v[34:35], v[26:27]
	v_pk_mul_f32 v[24:25], v[32:33], v[24:25]
	v_pk_fma_f32 v[30:31], v[32:33], v[16:17], v[30:31] neg_lo:[0,0,1] neg_hi:[0,0,1]
	v_pk_fma_f32 v[28:29], v[34:35], v[18:19], v[28:29] neg_lo:[0,0,1] neg_hi:[0,0,1]
	v_pk_fma_f32 v[16:17], v[36:37], v[16:17], v[24:25]
	v_pk_fma_f32 v[18:19], v[38:39], v[18:19], v[26:27]
	v_pk_add_f32 v[30:31], v[48:49], v[30:31]
	v_pk_add_f32 v[24:25], v[58:59], v[18:19]
	v_pk_add_f32 v[26:27], v[56:57], v[16:17]
	v_pk_mul_f32 v[16:17], v[38:39], v[38:39]
	v_pk_mul_f32 v[18:19], v[36:37], v[36:37]
	v_pk_mul_f32 v[48:49], v[6:7], v[6:7]
	v_pk_mul_f32 v[58:59], v[4:5], v[4:5]
	v_pk_fma_f32 v[82:83], v[34:35], v[34:35], v[16:17] neg_lo:[0,0,1] neg_hi:[0,0,1]
	v_pk_fma_f32 v[16:17], v[2:3], v[2:3], v[48:49] neg_lo:[0,0,1] neg_hi:[0,0,1]
	v_pk_fma_f32 v[48:49], v[32:33], v[32:33], v[18:19] neg_lo:[0,0,1] neg_hi:[0,0,1]
	v_pk_fma_f32 v[18:19], v[0:1], v[0:1], v[58:59] neg_lo:[0,0,1] neg_hi:[0,0,1]
	v_pk_add_f32 v[32:33], v[32:33], v[32:33]
	v_mov_b32_dpp v58, v74 row_shr:1 row_mask:0xf bank_mask:0xf bound_ctrl:1
	v_mov_b32_dpp v59, v75 row_shr:1 row_mask:0xf bank_mask:0xf bound_ctrl:1
	v_pk_mul_f32 v[80:81], v[44:45], v[44:45]
	v_pk_add_f32 v[34:35], v[34:35], v[34:35]
	v_pk_mul_f32 v[32:33], v[36:37], v[32:33]
	v_mov_b32_dpp v36, v64 row_shr:1 row_mask:0xf bank_mask:0xf bound_ctrl:1
	v_mov_b32_dpp v37, v65 row_shr:1 row_mask:0xf bank_mask:0xf bound_ctrl:1
	v_mov_b32_dpp v84, v76 row_shr:1 row_mask:0xf bank_mask:0xf bound_ctrl:1
	v_mov_b32_dpp v85, v77 row_shr:1 row_mask:0xf bank_mask:0xf bound_ctrl:1
	v_pk_mul_f32 v[88:89], v[44:45], v[58:59]
	v_pk_mul_f32 v[58:59], v[40:41], v[58:59]
	v_pk_mul_f32 v[56:57], v[46:47], v[46:47]
	v_pk_fma_f32 v[80:81], v[40:41], v[40:41], v[80:81] neg_lo:[0,0,1] neg_hi:[0,0,1]
	v_pk_mul_f32 v[34:35], v[38:39], v[34:35]
	v_mov_b32_dpp v38, v66 row_shr:1 row_mask:0xf bank_mask:0xf bound_ctrl:1
	v_mov_b32_dpp v39, v67 row_shr:1 row_mask:0xf bank_mask:0xf bound_ctrl:1
	v_pk_mul_f32 v[86:87], v[46:47], v[84:85]
	v_pk_fma_f32 v[88:89], v[40:41], v[36:37], v[88:89] neg_lo:[0,0,1] neg_hi:[0,0,1]
	v_pk_mul_f32 v[84:85], v[42:43], v[84:85]
	v_pk_fma_f32 v[36:37], v[44:45], v[36:37], v[58:59]
	v_pk_add_f32 v[40:41], v[40:41], v[40:41]
	v_mov_b32_dpp v58, v60 row_shr:1 row_mask:0xf bank_mask:0xf bound_ctrl:1
	v_mov_b32_dpp v59, v61 row_shr:1 row_mask:0xf bank_mask:0xf bound_ctrl:1
	v_pk_fma_f32 v[56:57], v[42:43], v[42:43], v[56:57] neg_lo:[0,0,1] neg_hi:[0,0,1]
	v_pk_fma_f32 v[86:87], v[42:43], v[38:39], v[86:87] neg_lo:[0,0,1] neg_hi:[0,0,1]
	v_pk_fma_f32 v[38:39], v[46:47], v[38:39], v[84:85]
	v_pk_add_f32 v[36:37], v[74:75], v[36:37]
	v_pk_add_f32 v[42:43], v[42:43], v[42:43]
	v_pk_mul_f32 v[40:41], v[44:45], v[40:41]
	v_mov_b32_dpp v44, v52 row_shr:1 row_mask:0xf bank_mask:0xf bound_ctrl:1
	v_mov_b32_dpp v45, v53 row_shr:1 row_mask:0xf bank_mask:0xf bound_ctrl:1
	v_mov_b32_dpp v74, v62 row_shr:1 row_mask:0xf bank_mask:0xf bound_ctrl:1
	v_mov_b32_dpp v75, v63 row_shr:1 row_mask:0xf bank_mask:0xf bound_ctrl:1
	v_pk_mul_f32 v[84:85], v[12:13], v[58:59]
	v_pk_mul_f32 v[58:59], v[8:9], v[58:59]
	v_pk_add_f32 v[28:29], v[50:51], v[28:29]
	v_pk_mul_f32 v[50:51], v[14:15], v[14:15]
	v_pk_mul_f32 v[78:79], v[12:13], v[12:13]
	v_pk_add_f32 v[38:39], v[76:77], v[38:39]
	v_pk_mul_f32 v[42:43], v[46:47], v[42:43]
	v_mov_b32_dpp v46, v54 row_shr:1 row_mask:0xf bank_mask:0xf bound_ctrl:1
	v_mov_b32_dpp v47, v55 row_shr:1 row_mask:0xf bank_mask:0xf bound_ctrl:1
	v_pk_mul_f32 v[76:77], v[14:15], v[74:75]
	v_pk_fma_f32 v[84:85], v[8:9], v[44:45], v[84:85] neg_lo:[0,0,1] neg_hi:[0,0,1]
	v_pk_mul_f32 v[74:75], v[10:11], v[74:75]
	v_pk_fma_f32 v[44:45], v[12:13], v[44:45], v[58:59]
	v_pk_fma_f32 v[50:51], v[10:11], v[10:11], v[50:51] neg_lo:[0,0,1] neg_hi:[0,0,1]
	v_pk_fma_f32 v[78:79], v[8:9], v[8:9], v[78:79] neg_lo:[0,0,1] neg_hi:[0,0,1]
	v_pk_fma_f32 v[76:77], v[10:11], v[46:47], v[76:77] neg_lo:[0,0,1] neg_hi:[0,0,1]
; template <int CTRL> DI f32x4 dpp4(const f32x4 v) { const float a0 = v[0], a1 = v[1], a2 = v[2], a3 = v[3]; const float b0 = DPPF(a0, CTRL), b1 = DPPF(a1, CTRL), b2 = DPPF(a2, CTRL), b3 = DPPF(a3, CTRL); return (f32x4){b0, b1, b2, b3}; }
; template <int D>
; DI void s5_scan_step(f32x4 (&Yr)[4], f32x4 (&Yi)[4], f32x4 (&Ar)[4], f32x4 (&Ai)[4]) {
; #pragma unroll
;     for (int m = 0; m < 4; ++m) {
;         const f32x4 sr = dpp4<0x110 + D>(Yr[m]), si = dpp4<0x110 + D>(Yi[m]);
;         Yr[m] += Ar[m] * sr - Ai[m] * si; Yi[m] += Ar[m] * si + Ai[m] * sr;
;         const f32x4 a2r = Ar[m] * Ar[m] - Ai[m] * Ai[m], a2i = 2.f * Ar[m] * Ai[m]; Ar[m] = a2r; Ai[m] = a2i; }
; }
	v_pk_fma_f32 v[46:47], v[14:15], v[46:47], v[74:75]
	v_pk_add_f32 v[44:45], v[60:61], v[44:45]
	v_pk_add_f32 v[10:11], v[10:11], v[10:11]
	v_pk_add_f32 v[8:9], v[8:9], v[8:9]
	v_mov_b32_dpp v58, v20 row_shr:1 row_mask:0xf bank_mask:0xf bound_ctrl:1
	v_mov_b32_dpp v59, v21 row_shr:1 row_mask:0xf bank_mask:0xf bound_ctrl:1
	v_mov_b32_dpp v60, v22 row_shr:1 row_mask:0xf bank_mask:0xf bound_ctrl:1
	v_mov_b32_dpp v61, v23 row_shr:1 row_mask:0xf bank_mask:0xf bound_ctrl:1
	v_pk_add_f32 v[46:47], v[62:63], v[46:47]
	v_pk_mul_f32 v[10:11], v[14:15], v[10:11]
	v_pk_mul_f32 v[8:9], v[12:13], v[8:9]
	v_mov_b32_dpp v12, v68 row_shr:1 row_mask:0xf bank_mask:0xf bound_ctrl:1
	v_mov_b32_dpp v13, v69 row_shr:1 row_mask:0xf bank_mask:0xf bound_ctrl:1
	v_mov_b32_dpp v14, v70 row_shr:1 row_mask:0xf bank_mask:0xf bound_ctrl:1
	v_mov_b32_dpp v15, v71 row_shr:1 row_mask:0xf bank_mask:0xf bound_ctrl:1
	v_pk_mul_f32 v[62:63], v[6:7], v[60:61]
	v_pk_mul_f32 v[74:75], v[4:5], v[58:59]
	v_pk_mul_f32 v[60:61], v[2:3], v[60:61]
	v_pk_mul_f32 v[58:59], v[0:1], v[58:59]
	v_pk_fma_f32 v[74:75], v[0:1], v[12:13], v[74:75] neg_lo:[0,0,1] neg_hi:[0,0,1]
	v_pk_fma_f32 v[62:63], v[2:3], v[14:15], v[62:63] neg_lo:[0,0,1] neg_hi:[0,0,1]
	v_pk_fma_f32 v[12:13], v[4:5], v[12:13], v[58:59]
	v_pk_fma_f32 v[14:15], v[6:7], v[14:15], v[60:61]
	v_pk_add_f32 v[2:3], v[2:3], v[2:3]
	v_pk_add_f32 v[0:1], v[0:1], v[0:1]
	v_pk_add_f32 v[66:67], v[66:67], v[86:87]
	v_pk_add_f32 v[64:65], v[64:65], v[88:89]
	v_pk_add_f32 v[54:55], v[54:55], v[76:77]
	v_pk_add_f32 v[52:53], v[52:53], v[84:85]
	v_pk_add_f32 v[62:63], v[70:71], v[62:63]
	v_pk_add_f32 v[68:69], v[68:69], v[74:75]
	v_pk_add_f32 v[14:15], v[22:23], v[14:15]
	v_pk_add_f32 v[12:13], v[20:21], v[12:13]
	v_pk_mul_f32 v[2:3], v[6:7], v[2:3]
	v_pk_mul_f32 v[0:1], v[4:5], v[0:1]
	v_mov_b32_dpp v22, v24 row_shr:2 row_mask:0xf bank_mask:0xf bound_ctrl:1
	v_mov_b32_dpp v23, v25 row_shr:2 row_mask:0xf bank_mask:0xf bound_ctrl:1
	v_mov_b32_dpp v6, v28 row_shr:2 row_mask:0xf bank_mask:0xf bound_ctrl:1
	v_mov_b32_dpp v7, v29 row_shr:2 row_mask:0xf bank_mask:0xf bound_ctrl:1
	v_mov_b32_dpp v20, v26 row_shr:2 row_mask:0xf bank_mask:0xf bound_ctrl:1
	v_mov_b32_dpp v21, v27 row_shr:2 row_mask:0xf bank_mask:0xf bound_ctrl:1
	v_pk_mul_f32 v[58:59], v[34:35], v[22:23]
	v_mov_b32_dpp v4, v30 row_shr:2 row_mask:0xf bank_mask:0xf bound_ctrl:1
	v_mov_b32_dpp v5, v31 row_shr:2 row_mask:0xf bank_mask:0xf bound_ctrl:1
	v_pk_mul_f32 v[60:61], v[32:33], v[20:21]
	v_pk_fma_f32 v[58:59], v[82:83], v[6:7], v[58:59] neg_lo:[0,0,1] neg_hi:[0,0,1]
	v_pk_mul_f32 v[20:21], v[48:49], v[20:21]
	v_pk_fma_f32 v[60:61], v[48:49], v[4:5], v[60:61] neg_lo:[0,0,1] neg_hi:[0,0,1]
	v_pk_add_f32 v[28:29], v[28:29], v[58:59]
	v_pk_mul_f32 v[22:23], v[82:83], v[22:23]
	v_pk_fma_f32 v[4:5], v[32:33], v[4:5], v[20:21]
	v_pk_mul_f32 v[20:21], v[82:83], v[82:83]
	v_pk_mul_f32 v[58:59], v[48:49], v[48:49]
	v_pk_add_f32 v[76:77], v[82:83], v[82:83]
	v_pk_add_f32 v[48:49], v[48:49], v[48:49]
	v_mov_b32_dpp v82, v36 row_shr:2 row_mask:0xf bank_mask:0xf bound_ctrl:1
	v_mov_b32_dpp v83, v37 row_shr:2 row_mask:0xf bank_mask:0xf bound_ctrl:1
	v_pk_fma_f32 v[58:59], v[32:33], v[32:33], v[58:59] neg_lo:[1,0,0] neg_hi:[1,0,0]
	v_pk_mul_f32 v[32:33], v[32:33], v[48:49]
	v_mov_b32_dpp v48, v64 row_shr:2 row_mask:0xf bank_mask:0xf bound_ctrl:1
	v_mov_b32_dpp v49, v65 row_shr:2 row_mask:0xf bank_mask:0xf bound_ctrl:1
	v_mov_b32_dpp v84, v38 row_shr:2 row_mask:0xf bank_mask:0xf bound_ctrl:1
	v_mov_b32_dpp v85, v39 row_shr:2 row_mask:0xf bank_mask:0xf bound_ctrl:1
	v_pk_mul_f32 v[88:89], v[40:41], v[82:83]
	v_pk_mul_f32 v[82:83], v[80:81], v[82:83]
	v_pk_fma_f32 v[6:7], v[34:35], v[6:7], v[22:23]
	v_pk_fma_f32 v[20:21], v[34:35], v[34:35], v[20:21] neg_lo:[1,0,0] neg_hi:[1,0,0]
	v_pk_mul_f32 v[34:35], v[34:35], v[76:77]
	v_mov_b32_dpp v76, v66 row_shr:2 row_mask:0xf bank_mask:0xf bound_ctrl:1
	v_mov_b32_dpp v77, v67 row_shr:2 row_mask:0xf bank_mask:0xf bound_ctrl:1
	v_pk_mul_f32 v[86:87], v[42:43], v[84:85]
	v_pk_fma_f32 v[88:89], v[80:81], v[48:49], v[88:89] neg_lo:[0,0,1] neg_hi:[0,0,1]
	v_pk_mul_f32 v[84:85], v[56:57], v[84:85]
	v_pk_fma_f32 v[48:49], v[40:41], v[48:49], v[82:83]
	v_pk_add_f32 v[4:5], v[26:27], v[4:5]
	v_pk_mul_f32 v[26:27], v[56:57], v[56:57]
	v_pk_mul_f32 v[74:75], v[80:81], v[80:81]
	v_pk_fma_f32 v[86:87], v[56:57], v[76:77], v[86:87] neg_lo:[0,0,1] neg_hi:[0,0,1]
	v_pk_fma_f32 v[76:77], v[42:43], v[76:77], v[84:85]
	v_pk_add_f32 v[48:49], v[36:37], v[48:49]
	v_pk_add_f32 v[36:37], v[80:81], v[80:81]
	v_pk_add_f32 v[76:77], v[38:39], v[76:77]
	v_pk_fma_f32 v[82:83], v[42:43], v[42:43], v[26:27] neg_lo:[1,0,0] neg_hi:[1,0,0]
	v_pk_fma_f32 v[74:75], v[40:41], v[40:41], v[74:75] neg_lo:[1,0,0] neg_hi:[1,0,0]
	v_pk_add_f32 v[26:27], v[56:57], v[56:57]
	v_pk_mul_f32 v[80:81], v[40:41], v[36:37]
	v_mov_b32_dpp v38, v44 row_shr:2 row_mask:0xf bank_mask:0xf bound_ctrl:1
	v_mov_b32_dpp v39, v45 row_shr:2 row_mask:0xf bank_mask:0xf bound_ctrl:1
	v_mov_b32_dpp v40, v46 row_shr:2 row_mask:0xf bank_mask:0xf bound_ctrl:1
	v_mov_b32_dpp v41, v47 row_shr:2 row_mask:0xf bank_mask:0xf bound_ctrl:1
	v_pk_mul_f32 v[56:57], v[42:43], v[26:27]
	v_mov_b32_dpp v26, v52 row_shr:2 row_mask:0xf bank_mask:0xf bound_ctrl:1
	v_mov_b32_dpp v27, v53 row_shr:2 row_mask:0xf bank_mask:0xf bound_ctrl:1
	v_mov_b32_dpp v36, v54 row_shr:2 row_mask:0xf bank_mask:0xf bound_ctrl:1
	v_mov_b32_dpp v37, v55 row_shr:2 row_mask:0xf bank_mask:0xf bound_ctrl:1
	v_pk_mul_f32 v[42:43], v[10:11], v[40:41]
	v_pk_mul_f32 v[84:85], v[8:9], v[38:39]
	v_pk_mul_f32 v[40:41], v[50:51], v[40:41]
	v_pk_mul_f32 v[38:39], v[78:79], v[38:39]
; template <int CTRL> DI f32x4 dpp4(const f32x4 v) { const float a0 = v[0], a1 = v[1], a2 = v[2], a3 = v[3]; const float b0 = DPPF(a0, CTRL), b1 = DPPF(a1, CTRL), b2 = DPPF(a2, CTRL), b3 = DPPF(a3, CTRL); return (f32x4){b0, b1, b2, b3}; }
; template <int D>
; DI void s5_scan_step(f32x4 (&Yr)[4], f32x4 (&Yi)[4], f32x4 (&Ar)[4], f32x4 (&Ai)[4]) {
; #pragma unroll
;     for (int m = 0; m < 4; ++m) {
;         const f32x4 sr = dpp4<0x110 + D>(Yr[m]), si = dpp4<0x110 + D>(Yi[m]);
;         Yr[m] += Ar[m] * sr - Ai[m] * si; Yi[m] += Ar[m] * si + Ai[m] * sr;
;         const f32x4 a2r = Ar[m] * Ar[m] - Ai[m] * Ai[m], a2i = 2.f * Ar[m] * Ai[m]; Ar[m] = a2r; Ai[m] = a2i; }
; }
	v_pk_fma_f32 v[84:85], v[78:79], v[26:27], v[84:85] neg_lo:[0,0,1] neg_hi:[0,0,1]
	v_pk_fma_f32 v[42:43], v[50:51], v[36:37], v[42:43] neg_lo:[0,0,1] neg_hi:[0,0,1]
	v_pk_fma_f32 v[26:27], v[8:9], v[26:27], v[38:39]
	v_pk_fma_f32 v[36:37], v[10:11], v[36:37], v[40:41]
	v_pk_add_f32 v[66:67], v[66:67], v[86:87]
	v_pk_add_f32 v[52:53], v[52:53], v[84:85]
	v_pk_add_f32 v[84:85], v[46:47], v[36:37]
	v_pk_add_f32 v[86:87], v[44:45], v[26:27]
	v_pk_add_f32 v[26:27], v[50:51], v[50:51]
	v_pk_add_f32 v[36:37], v[78:79], v[78:79]
	v_pk_add_f32 v[6:7], v[24:25], v[6:7]
	v_pk_mul_f32 v[24:25], v[50:51], v[50:51]
	v_pk_mul_f32 v[70:71], v[78:79], v[78:79]
	v_pk_mul_f32 v[50:51], v[10:11], v[26:27]
	v_pk_mul_f32 v[78:79], v[8:9], v[36:37]
	v_mov_b32_dpp v26, v12 row_shr:2 row_mask:0xf bank_mask:0xf bound_ctrl:1
	v_mov_b32_dpp v27, v13 row_shr:2 row_mask:0xf bank_mask:0xf bound_ctrl:1
	v_mov_b32_dpp v36, v14 row_shr:2 row_mask:0xf bank_mask:0xf bound_ctrl:1
	v_mov_b32_dpp v37, v15 row_shr:2 row_mask:0xf bank_mask:0xf bound_ctrl:1
	v_pk_fma_f32 v[24:25], v[10:11], v[10:11], v[24:25] neg_lo:[1,0,0] neg_hi:[1,0,0]
	v_pk_fma_f32 v[70:71], v[8:9], v[8:9], v[70:71] neg_lo:[1,0,0] neg_hi:[1,0,0]
	v_mov_b32_dpp v8, v68 row_shr:2 row_mask:0xf bank_mask:0xf bound_ctrl:1
	v_mov_b32_dpp v9, v69 row_shr:2 row_mask:0xf bank_mask:0xf bound_ctrl:1
	v_mov_b32_dpp v10, v62 row_shr:2 row_mask:0xf bank_mask:0xf bound_ctrl:1
	v_mov_b32_dpp v11, v63 row_shr:2 row_mask:0xf bank_mask:0xf bound_ctrl:1
	v_pk_mul_f32 v[38:39], v[2:3], v[36:37]
	v_pk_mul_f32 v[40:41], v[0:1], v[26:27]
	v_pk_mul_f32 v[36:37], v[16:17], v[36:37]
	v_pk_mul_f32 v[26:27], v[18:19], v[26:27]
	v_pk_fma_f32 v[40:41], v[18:19], v[8:9], v[40:41] neg_lo:[0,0,1] neg_hi:[0,0,1]
	v_pk_fma_f32 v[38:39], v[16:17], v[10:11], v[38:39] neg_lo:[0,0,1] neg_hi:[0,0,1]
	v_pk_fma_f32 v[8:9], v[0:1], v[8:9], v[26:27]
	v_pk_fma_f32 v[10:11], v[2:3], v[10:11], v[36:37]
	v_pk_add_f32 v[30:31], v[30:31], v[60:61]
	v_pk_mul_f32 v[22:23], v[16:17], v[16:17]
	v_pk_mul_f32 v[60:61], v[18:19], v[18:19]
	v_pk_add_f32 v[64:65], v[64:65], v[88:89]
	v_pk_add_f32 v[88:89], v[14:15], v[10:11]
	v_pk_add_f32 v[90:91], v[12:13], v[8:9]
	v_pk_add_f32 v[8:9], v[16:17], v[16:17]
	v_pk_add_f32 v[10:11], v[18:19], v[18:19]
	v_pk_add_f32 v[54:55], v[54:55], v[42:43]
	v_pk_add_f32 v[62:63], v[62:63], v[38:39]
	v_pk_add_f32 v[68:69], v[68:69], v[40:41]
	v_pk_fma_f32 v[92:93], v[2:3], v[2:3], v[22:23] neg_lo:[1,0,0] neg_hi:[1,0,0]
	v_pk_fma_f32 v[60:61], v[0:1], v[0:1], v[60:61] neg_lo:[1,0,0] neg_hi:[1,0,0]
	v_pk_mul_f32 v[94:95], v[2:3], v[8:9]
	v_pk_mul_f32 v[96:97], v[0:1], v[10:11]
	v_mov_b32_dpp v8, v4 row_shr:4 row_mask:0xf bank_mask:0xf bound_ctrl:1
	v_mov_b32_dpp v9, v5 row_shr:4 row_mask:0xf bank_mask:0xf bound_ctrl:1
	v_mov_b32_dpp v0, v30 row_shr:4 row_mask:0xf bank_mask:0xf bound_ctrl:1
	v_mov_b32_dpp v1, v31 row_shr:4 row_mask:0xf bank_mask:0xf bound_ctrl:1
	v_mov_b32_dpp v10, v6 row_shr:4 row_mask:0xf bank_mask:0xf bound_ctrl:1
	v_mov_b32_dpp v11, v7 row_shr:4 row_mask:0xf bank_mask:0xf bound_ctrl:1
	v_pk_mul_f32 v[14:15], v[32:33], v[8:9]
	v_mov_b32_dpp v2, v28 row_shr:4 row_mask:0xf bank_mask:0xf bound_ctrl:1
	v_mov_b32_dpp v3, v29 row_shr:4 row_mask:0xf bank_mask:0xf bound_ctrl:1
	v_pk_mul_f32 v[12:13], v[34:35], v[10:11]
	v_pk_fma_f32 v[14:15], v[58:59], v[0:1], v[14:15] neg_lo:[0,0,1] neg_hi:[0,0,1]
	v_pk_mul_f32 v[8:9], v[58:59], v[8:9]
	v_pk_fma_f32 v[12:13], v[20:21], v[2:3], v[12:13] neg_lo:[0,0,1] neg_hi:[0,0,1]
	v_pk_add_f32 v[26:27], v[30:31], v[14:15]
	v_pk_mul_f32 v[10:11], v[20:21], v[10:11]
	v_pk_fma_f32 v[0:1], v[32:33], v[0:1], v[8:9]
	v_mov_b32_dpp v14, v76 row_shr:4 row_mask:0xf bank_mask:0xf bound_ctrl:1
	v_mov_b32_dpp v15, v77 row_shr:4 row_mask:0xf bank_mask:0xf bound_ctrl:1
	v_pk_add_f32 v[22:23], v[28:29], v[12:13]
	v_pk_fma_f32 v[2:3], v[34:35], v[2:3], v[10:11]
	v_pk_add_f32 v[30:31], v[4:5], v[0:1]
	v_pk_mul_f32 v[0:1], v[34:35], v[34:35]
	v_mov_b32_dpp v10, v66 row_shr:4 row_mask:0xf bank_mask:0xf bound_ctrl:1
	v_mov_b32_dpp v11, v67 row_shr:4 row_mask:0xf bank_mask:0xf bound_ctrl:1
	v_mov_b32_dpp v12, v48 row_shr:4 row_mask:0xf bank_mask:0xf bound_ctrl:1
	v_mov_b32_dpp v13, v49 row_shr:4 row_mask:0xf bank_mask:0xf bound_ctrl:1
	v_pk_mul_f32 v[16:17], v[56:57], v[14:15]
	v_pk_add_f32 v[28:29], v[6:7], v[2:3]
	v_pk_fma_f32 v[0:1], v[20:21], v[20:21], v[0:1] neg_lo:[0,0,1] neg_hi:[0,0,1]
	v_pk_add_f32 v[4:5], v[20:21], v[20:21]
	v_pk_add_f32 v[6:7], v[58:59], v[58:59]
	v_mov_b32_dpp v8, v64 row_shr:4 row_mask:0xf bank_mask:0xf bound_ctrl:1
	v_mov_b32_dpp v9, v65 row_shr:4 row_mask:0xf bank_mask:0xf bound_ctrl:1
	v_pk_mul_f32 v[18:19], v[80:81], v[12:13]
	v_pk_fma_f32 v[16:17], v[82:83], v[10:11], v[16:17] neg_lo:[0,0,1] neg_hi:[0,0,1]
	v_mov_b32_dpp v20, v86 row_shr:4 row_mask:0xf bank_mask:0xf bound_ctrl:1
	v_mov_b32_dpp v21, v87 row_shr:4 row_mask:0xf bank_mask:0xf bound_ctrl:1
	v_pk_mul_f32 v[2:3], v[32:33], v[32:33]
	v_pk_mul_f32 v[6:7], v[32:33], v[6:7]
	v_pk_fma_f32 v[18:19], v[74:75], v[8:9], v[18:19] neg_lo:[0,0,1] neg_hi:[0,0,1]
	v_pk_add_f32 v[36:37], v[66:67], v[16:17]
	v_pk_mul_f32 v[12:13], v[74:75], v[12:13]
	v_mov_b32_dpp v16, v52 row_shr:4 row_mask:0xf bank_mask:0xf bound_ctrl:1
	v_mov_b32_dpp v17, v53 row_shr:4 row_mask:0xf bank_mask:0xf bound_ctrl:1
	v_mov_b32_dpp v32, v84 row_shr:4 row_mask:0xf bank_mask:0xf bound_ctrl:1
	v_mov_b32_dpp v33, v85 row_shr:4 row_mask:0xf bank_mask:0xf bound_ctrl:1
	v_pk_mul_f32 v[44:45], v[78:79], v[20:21]
	v_pk_mul_f32 v[20:21], v[70:71], v[20:21]
	v_pk_mul_f32 v[4:5], v[34:35], v[4:5]
	v_pk_add_f32 v[38:39], v[64:65], v[18:19]
; template <int CTRL> DI f32x4 dpp4(const f32x4 v) { const float a0 = v[0], a1 = v[1], a2 = v[2], a3 = v[3]; const float b0 = DPPF(a0, CTRL), b1 = DPPF(a1, CTRL), b2 = DPPF(a2, CTRL), b3 = DPPF(a3, CTRL); return (f32x4){b0, b1, b2, b3}; }
; template <int D>
; DI void s5_scan_step(f32x4 (&Yr)[4], f32x4 (&Yi)[4], f32x4 (&Ar)[4], f32x4 (&Ai)[4]) {
; #pragma unroll
;     for (int m = 0; m < 4; ++m) {
;         const f32x4 sr = dpp4<0x110 + D>(Yr[m]), si = dpp4<0x110 + D>(Yi[m]);
;         Yr[m] += Ar[m] * sr - Ai[m] * si; Yi[m] += Ar[m] * si + Ai[m] * sr;
;         const f32x4 a2r = Ar[m] * Ar[m] - Ai[m] * Ai[m], a2i = 2.f * Ar[m] * Ai[m]; Ar[m] = a2r; Ai[m] = a2i; }
; }
; template <bool POST>
; DI void s5_phase(const Frame& F, const CAS Args& a, int l, int first, int stride) {
;     ...
;         if (n == 15) {
	v_pk_fma_f32 v[8:9], v[80:81], v[8:9], v[12:13]
	v_mov_b32_dpp v18, v54 row_shr:4 row_mask:0xf bank_mask:0xf bound_ctrl:1
	v_mov_b32_dpp v19, v55 row_shr:4 row_mask:0xf bank_mask:0xf bound_ctrl:1
	v_pk_mul_f32 v[34:35], v[50:51], v[32:33]
	v_pk_fma_f32 v[46:47], v[70:71], v[16:17], v[44:45] neg_lo:[0,0,1] neg_hi:[0,0,1]
	v_pk_mul_f32 v[32:33], v[24:25], v[32:33]
	v_pk_fma_f32 v[16:17], v[78:79], v[16:17], v[20:21]
	v_pk_add_f32 v[20:21], v[24:25], v[24:25]
	v_pk_fma_f32 v[2:3], v[58:59], v[58:59], v[2:3] neg_lo:[0,0,1] neg_hi:[0,0,1]
	v_pk_mul_f32 v[14:15], v[82:83], v[14:15]
	v_pk_add_f32 v[42:43], v[48:49], v[8:9]
	v_pk_add_f32 v[12:13], v[82:83], v[82:83]
	v_pk_fma_f32 v[34:35], v[24:25], v[18:19], v[34:35] neg_lo:[0,0,1] neg_hi:[0,0,1]
	v_pk_fma_f32 v[18:19], v[50:51], v[18:19], v[32:33]
	v_pk_add_f32 v[58:59], v[86:87], v[16:17]
	v_pk_mul_f32 v[16:17], v[50:51], v[50:51]
	v_pk_mul_f32 v[20:21], v[50:51], v[20:21]
	v_mov_b32_dpp v48, v90 row_shr:4 row_mask:0xf bank_mask:0xf bound_ctrl:1
	v_mov_b32_dpp v49, v91 row_shr:4 row_mask:0xf bank_mask:0xf bound_ctrl:1
	v_mov_b32_dpp v50, v88 row_shr:4 row_mask:0xf bank_mask:0xf bound_ctrl:1
	v_mov_b32_dpp v51, v89 row_shr:4 row_mask:0xf bank_mask:0xf bound_ctrl:1
	v_pk_fma_f32 v[10:11], v[56:57], v[10:11], v[14:15]
	v_pk_mul_f32 v[8:9], v[56:57], v[56:57]
	v_pk_mul_f32 v[12:13], v[56:57], v[12:13]
	v_pk_add_f32 v[44:45], v[54:55], v[34:35]
	v_mov_b32_dpp v32, v68 row_shr:4 row_mask:0xf bank_mask:0xf bound_ctrl:1
	v_mov_b32_dpp v33, v69 row_shr:4 row_mask:0xf bank_mask:0xf bound_ctrl:1
	v_mov_b32_dpp v34, v62 row_shr:4 row_mask:0xf bank_mask:0xf bound_ctrl:1
	v_mov_b32_dpp v35, v63 row_shr:4 row_mask:0xf bank_mask:0xf bound_ctrl:1
	v_pk_mul_f32 v[54:55], v[94:95], v[50:51]
	v_pk_mul_f32 v[56:57], v[96:97], v[48:49]
	v_pk_mul_f32 v[50:51], v[92:93], v[50:51]
	v_pk_mul_f32 v[48:49], v[60:61], v[48:49]
	v_pk_add_f32 v[14:15], v[74:75], v[74:75]
	v_pk_fma_f32 v[56:57], v[60:61], v[32:33], v[56:57] neg_lo:[0,0,1] neg_hi:[0,0,1]
	v_pk_fma_f32 v[54:55], v[92:93], v[34:35], v[54:55] neg_lo:[0,0,1] neg_hi:[0,0,1]
	v_pk_fma_f32 v[32:33], v[96:97], v[32:33], v[48:49]
	v_pk_fma_f32 v[34:35], v[94:95], v[34:35], v[50:51]
	v_pk_add_f32 v[40:41], v[76:77], v[10:11]
	v_pk_mul_f32 v[10:11], v[80:81], v[80:81]
	v_pk_mul_f32 v[14:15], v[80:81], v[14:15]
	v_pk_add_f32 v[46:47], v[52:53], v[46:47]
	v_pk_add_f32 v[52:53], v[84:85], v[18:19]
	v_pk_mul_f32 v[18:19], v[78:79], v[78:79]
	v_pk_fma_f32 v[16:17], v[24:25], v[24:25], v[16:17] neg_lo:[0,0,1] neg_hi:[0,0,1]
	v_pk_add_f32 v[24:25], v[70:71], v[70:71]
	v_pk_add_f32 v[80:81], v[88:89], v[34:35]
	v_pk_add_f32 v[84:85], v[90:91], v[32:33]
	v_pk_mul_f32 v[32:33], v[94:95], v[94:95]
	v_pk_mul_f32 v[34:35], v[96:97], v[96:97]
	v_pk_add_f32 v[48:49], v[92:93], v[92:93]
	v_pk_add_f32 v[50:51], v[60:61], v[60:61]
	v_pk_fma_f32 v[8:9], v[82:83], v[82:83], v[8:9] neg_lo:[0,0,1] neg_hi:[0,0,1]
	v_pk_fma_f32 v[10:11], v[74:75], v[74:75], v[10:11] neg_lo:[0,0,1] neg_hi:[0,0,1]
	v_pk_fma_f32 v[18:19], v[70:71], v[70:71], v[18:19] neg_lo:[0,0,1] neg_hi:[0,0,1]
	v_pk_mul_f32 v[24:25], v[78:79], v[24:25]
	v_pk_add_f32 v[74:75], v[62:63], v[54:55]
	v_pk_add_f32 v[76:77], v[68:69], v[56:57]
	v_pk_fma_f32 v[32:33], v[92:93], v[92:93], v[32:33] neg_lo:[0,0,1] neg_hi:[0,0,1]
	v_pk_fma_f32 v[34:35], v[60:61], v[60:61], v[34:35] neg_lo:[0,0,1] neg_hi:[0,0,1]
	v_pk_mul_f32 v[60:61], v[94:95], v[48:49]
	v_pk_mul_f32 v[62:63], v[96:97], v[50:51]
	v_mov_b32_dpp v48, v26 row_shr:8 row_mask:0xf bank_mask:0xf bound_ctrl:1
	v_mov_b32_dpp v49, v27 row_shr:8 row_mask:0xf bank_mask:0xf bound_ctrl:1
	v_mov_b32_dpp v50, v22 row_shr:8 row_mask:0xf bank_mask:0xf bound_ctrl:1
	v_mov_b32_dpp v51, v23 row_shr:8 row_mask:0xf bank_mask:0xf bound_ctrl:1
	v_mov_b32_dpp v54, v30 row_shr:8 row_mask:0xf bank_mask:0xf bound_ctrl:1
	v_mov_b32_dpp v55, v31 row_shr:8 row_mask:0xf bank_mask:0xf bound_ctrl:1
	v_mov_b32_dpp v56, v28 row_shr:8 row_mask:0xf bank_mask:0xf bound_ctrl:1
	v_mov_b32_dpp v57, v29 row_shr:8 row_mask:0xf bank_mask:0xf bound_ctrl:1
	v_mov_b32_dpp v64, v38 row_shr:8 row_mask:0xf bank_mask:0xf bound_ctrl:1
	v_mov_b32_dpp v65, v39 row_shr:8 row_mask:0xf bank_mask:0xf bound_ctrl:1
	v_mov_b32_dpp v66, v36 row_shr:8 row_mask:0xf bank_mask:0xf bound_ctrl:1
	v_mov_b32_dpp v67, v37 row_shr:8 row_mask:0xf bank_mask:0xf bound_ctrl:1
	v_mov_b32_dpp v68, v42 row_shr:8 row_mask:0xf bank_mask:0xf bound_ctrl:1
	v_mov_b32_dpp v69, v43 row_shr:8 row_mask:0xf bank_mask:0xf bound_ctrl:1
	v_mov_b32_dpp v70, v40 row_shr:8 row_mask:0xf bank_mask:0xf bound_ctrl:1
	v_mov_b32_dpp v71, v41 row_shr:8 row_mask:0xf bank_mask:0xf bound_ctrl:1
	v_mov_b32_dpp v78, v46 row_shr:8 row_mask:0xf bank_mask:0xf bound_ctrl:1
	v_mov_b32_dpp v79, v47 row_shr:8 row_mask:0xf bank_mask:0xf bound_ctrl:1
	v_mov_b32_dpp v82, v44 row_shr:8 row_mask:0xf bank_mask:0xf bound_ctrl:1
	v_mov_b32_dpp v83, v45 row_shr:8 row_mask:0xf bank_mask:0xf bound_ctrl:1
	v_mov_b32_dpp v86, v58 row_shr:8 row_mask:0xf bank_mask:0xf bound_ctrl:1
	v_mov_b32_dpp v87, v59 row_shr:8 row_mask:0xf bank_mask:0xf bound_ctrl:1
	v_mov_b32_dpp v88, v52 row_shr:8 row_mask:0xf bank_mask:0xf bound_ctrl:1
	v_mov_b32_dpp v89, v53 row_shr:8 row_mask:0xf bank_mask:0xf bound_ctrl:1
	v_mov_b32_dpp v90, v76 row_shr:8 row_mask:0xf bank_mask:0xf bound_ctrl:1
	v_mov_b32_dpp v91, v77 row_shr:8 row_mask:0xf bank_mask:0xf bound_ctrl:1
	v_mov_b32_dpp v92, v74 row_shr:8 row_mask:0xf bank_mask:0xf bound_ctrl:1
	v_mov_b32_dpp v93, v75 row_shr:8 row_mask:0xf bank_mask:0xf bound_ctrl:1
	v_mov_b32_dpp v94, v84 row_shr:8 row_mask:0xf bank_mask:0xf bound_ctrl:1
	v_mov_b32_dpp v95, v85 row_shr:8 row_mask:0xf bank_mask:0xf bound_ctrl:1
	v_mov_b32_dpp v96, v80 row_shr:8 row_mask:0xf bank_mask:0xf bound_ctrl:1
	v_mov_b32_dpp v97, v81 row_shr:8 row_mask:0xf bank_mask:0xf bound_ctrl:1
	s_and_saveexec_b64 s[4:5], vcc
	s_cbranch_execz .LBB0_726
; #define LAS __attribute__((address_space(3)))
; #define SB() __builtin_amdgcn_sched_barrier(0)
; template <bool POST>
; DI void s5_phase(const Frame& F, const CAS Args& a, int l, int first, int stride) {
;     ...
;         s5_scan_step<1>(Yr, Yi, Ar, Ai); SB(); s5_scan_step<2>(Yr, Yi, Ar, Ai); SB(); s5_scan_step<4>(Yr, Yi, Ar, Ai); SB(); s5_scan_step<8>(Yr, Yi, Ar, Ai); SB();
;         if (n == 15) {
; #pragma unroll
;             for (int m = 0; m < 4; ++m) { *(LAS f32x4*)(TW + w * 128 + 16 * m + 4 * kg) = Yr[m]; *(LAS f32x4*)(TW + w * 128 + 64 + 16 * m + 4 * kg) = Yi[m]; } }
	v_pk_mul_f32 v[102:103], v[32:33], v[96:97]
	v_pk_mul_f32 v[104:105], v[34:35], v[94:95]
	v_pk_fma_f32 v[106:107], v[60:61], v[92:93], v[102:103]
	v_pk_fma_f32 v[102:103], v[62:63], v[90:91], v[104:105]
	v_pk_add_f32 v[104:105], v[80:81], v[106:107]
	v_pk_add_f32 v[102:103], v[84:85], v[102:103]
	v_pk_mul_f32 v[80:81], v[60:61], v[96:97]
	v_pk_mul_f32 v[84:85], v[62:63], v[94:95]
	v_pk_fma_f32 v[80:81], v[32:33], v[92:93], v[80:81] neg_lo:[0,0,1] neg_hi:[0,0,1]
	v_pk_fma_f32 v[84:85], v[34:35], v[90:91], v[84:85] neg_lo:[0,0,1] neg_hi:[0,0,1]
	v_pk_add_f32 v[92:93], v[74:75], v[80:81]
	v_pk_add_f32 v[90:91], v[76:77], v[84:85]
	v_pk_mul_f32 v[74:75], v[16:17], v[88:89]
	v_pk_mul_f32 v[76:77], v[18:19], v[86:87]
	v_pk_fma_f32 v[80:81], v[20:21], v[82:83], v[74:75]
	v_pk_fma_f32 v[74:75], v[24:25], v[78:79], v[76:77]
	v_pk_add_f32 v[76:77], v[52:53], v[80:81]
	v_pk_add_f32 v[74:75], v[58:59], v[74:75]
	v_pk_mul_f32 v[52:53], v[20:21], v[88:89]
	v_pk_mul_f32 v[58:59], v[24:25], v[86:87]
	v_pk_fma_f32 v[52:53], v[16:17], v[82:83], v[52:53] neg_lo:[0,0,1] neg_hi:[0,0,1]
	v_pk_fma_f32 v[58:59], v[18:19], v[78:79], v[58:59] neg_lo:[0,0,1] neg_hi:[0,0,1]
	v_pk_add_f32 v[80:81], v[44:45], v[52:53]
	v_pk_add_f32 v[78:79], v[46:47], v[58:59]
	v_pk_mul_f32 v[44:45], v[8:9], v[70:71]
	v_pk_mul_f32 v[46:47], v[10:11], v[68:69]
	v_pk_fma_f32 v[44:45], v[12:13], v[66:67], v[44:45]
	v_pk_fma_f32 v[46:47], v[14:15], v[64:65], v[46:47]
	v_pk_add_f32 v[44:45], v[40:41], v[44:45]
	v_pk_add_f32 v[42:43], v[42:43], v[46:47]
	v_pk_mul_f32 v[40:41], v[12:13], v[70:71]
	v_pk_mul_f32 v[46:47], v[14:15], v[68:69]
	v_pk_fma_f32 v[40:41], v[8:9], v[66:67], v[40:41] neg_lo:[0,0,1] neg_hi:[0,0,1]
	v_pk_fma_f32 v[46:47], v[10:11], v[64:65], v[46:47] neg_lo:[0,0,1] neg_hi:[0,0,1]
	v_pk_add_f32 v[40:41], v[36:37], v[40:41]
	v_pk_add_f32 v[38:39], v[38:39], v[46:47]
	v_pk_mul_f32 v[36:37], v[0:1], v[56:57]
	v_pk_mul_f32 v[46:47], v[2:3], v[54:55]
	v_pk_fma_f32 v[36:37], v[4:5], v[50:51], v[36:37]
	v_pk_fma_f32 v[46:47], v[6:7], v[48:49], v[46:47]
	v_pk_add_f32 v[66:67], v[28:29], v[36:37]
	v_pk_add_f32 v[64:65], v[30:31], v[46:47]
	v_pk_mul_f32 v[28:29], v[4:5], v[56:57]
	v_pk_mul_f32 v[30:31], v[6:7], v[54:55]
	v_readlane_b32 s14, v253, 53
	v_pk_fma_f32 v[28:29], v[0:1], v[50:51], v[28:29] neg_lo:[0,0,1] neg_hi:[0,0,1]
	v_pk_fma_f32 v[30:31], v[2:3], v[48:49], v[30:31] neg_lo:[0,0,1] neg_hi:[0,0,1]
	s_add_i32 s14, s16, s14
	v_pk_add_f32 v[26:27], v[26:27], v[30:31]
	v_pk_add_f32 v[28:29], v[22:23], v[28:29]
	v_lshl_add_u32 v22, v72, 2, s14
	ds_write_b128 v22, v[26:29]
	ds_write_b128 v22, v[64:67] offset:256
	ds_write_b128 v22, v[38:41] offset:64
	ds_write_b128 v22, v[42:45] offset:320
	ds_write_b128 v22, v[78:81] offset:128
	ds_write_b128 v22, v[74:77] offset:384
	ds_write_b128 v22, v[90:93] offset:192
	ds_write_b128 v22, v[102:105] offset:448
